# prep pass 3: rmsnorm statistics reduced with DPP (row_shr scan + row_bcast, row_ror butterflies) instead of ds_bpermute butterflies (28 dependent LDS-crossbar hops per loop iteration)
# speedup vs baseline: 1.0022x; 1.0022x over previous
.LBB0_1189:
	s_or_b64 exec, exec, s[46:47]
	s_mov_b64 s[0:1], 0xb134000
	s_waitcnt vmcnt(2)
	s_and_saveexec_b64 s[98:99], s[4:5]
	v_lshl_or_b32 v73, v99, 16, v98
	v_lshl_or_b32 v41, v101, 16, v100
	s_or_b64 exec, exec, s[98:99]
	v_and_b32_e32 v83, 0xffff0000, v60
	v_and_b32_e32 v65, 0xffff0000, v61
	v_and_b32_e32 v64, s0, v60
	v_lshlrev_b32_e32 v82, 16, v60
	v_mul_f32_e32 v60, v83, v83
	v_lshlrev_b32_e32 v66, 16, v61
	v_mov_b32_e32 v67, v65
	v_pk_fma_f32 v[60:61], v[82:83], v[82:83], v[60:61] op_sel_hi:[1,1,0]
	s_waitcnt vmcnt(1)
	v_lshlrev_b32_e32 v84, 16, v62
	v_and_b32_e32 v85, 0xffff0000, v62
	v_pk_mul_f32 v[64:65], v[64:65], v[64:65]
	v_pk_fma_f32 v[60:61], v[66:67], v[66:67], v[60:61]
	v_pk_mul_f32 v[62:63], v[84:85], v[84:85]
	v_cndmask_b32_e64 v53, v213, v214, s[16:17]
	v_mov_b32_e32 v64, v62
	v_pk_mov_b32 v[60:61], v[62:63], v[60:61] op_sel:[1,0]
	v_lshl_add_u64 v[16:17], v[56:57], 0, s[0:1]
	v_pk_add_f32 v[60:61], v[64:65], v[60:61]
	v_readlane_b32 s0, v254, 29
	v_readlane_b32 s1, v254, 30
	v_readlane_b32 s2, v254, 25
	v_readlane_b32 s3, v254, 26
	s_waitcnt lgkmcnt(0)
	s_nop 1
	v_add_f32_dpp v60, v60, v60 row_shr:1 row_mask:0xf bank_mask:0xf bound_ctrl:1
	v_add_f32_dpp v61, v61, v61 row_shr:1 row_mask:0xf bank_mask:0xf bound_ctrl:1
	s_nop 0
	v_add_f32_dpp v60, v60, v60 row_shr:2 row_mask:0xf bank_mask:0xf bound_ctrl:1
	v_add_f32_dpp v61, v61, v61 row_shr:2 row_mask:0xf bank_mask:0xf bound_ctrl:1
	s_nop 0
	v_add_f32_dpp v60, v60, v60 row_shr:4 row_mask:0xf bank_mask:0xf bound_ctrl:1
	v_add_f32_dpp v61, v61, v61 row_shr:4 row_mask:0xf bank_mask:0xf bound_ctrl:1
	s_nop 0
	v_add_f32_dpp v60, v60, v60 row_shr:8 row_mask:0xf bank_mask:0xf bound_ctrl:1
	v_add_f32_dpp v61, v61, v61 row_shr:8 row_mask:0xf bank_mask:0xf bound_ctrl:1
	s_nop 0
	v_add_f32_dpp v60, v60, v60 row_bcast:15 row_mask:0xa bank_mask:0xf
	v_add_f32_dpp v61, v61, v61 row_bcast:15 row_mask:0xa bank_mask:0xf
	s_nop 0
	v_add_f32_dpp v60, v60, v60 row_bcast:31 row_mask:0xc bank_mask:0xf
	v_add_f32_dpp v61, v61, v61 row_bcast:31 row_mask:0xc bank_mask:0xf
	s_nop 0
	v_readlane_b32 s98, v60, 63
	v_readlane_b32 s99, v61, 63
	s_nop 0
	v_mov_b32_e32 v60, s98
	v_mov_b32_e32 v61, s99
	s_load_dwordx2 s[2:3], s[2:3], 0x118
	s_waitcnt lgkmcnt(0)
	s_waitcnt lgkmcnt(0)
	s_waitcnt lgkmcnt(0)
	v_ashrrev_i32_e32 v63, 7, v70
	v_and_b32_e32 v62, v53, v70
	v_and_b32_e32 v53, -2, v63
	v_cndmask_b32_e64 v53, 0, v53, s[16:17]
	s_waitcnt lgkmcnt(0)
	v_add_u32_e32 v86, s0, v53
	s_brev_b32 s0, 60
	s_mov_b32 s1, 0x3b800000
	v_ashrrev_i32_e32 v87, 31, v86
	s_waitcnt lgkmcnt(0)
	v_lshlrev_b64 v[86:87], 8, v[86:87]
	v_pk_fma_f32 v[60:61], v[60:61], s[0:1], v[162:163] op_sel_hi:[1,1,0]
	s_mov_b32 s0, 0x800000
	v_mul_f32_e32 v53, 0x4b800000, v61
	v_cmp_gt_f32_e32 vcc, s0, v61
	v_mov_b32_e32 v63, v1
	v_lshl_add_u64 v[64:65], v[86:87], 0, v[62:63]
	v_cndmask_b32_e32 v53, v61, v53, vcc
	v_rsq_f32_e32 v53, v53
	v_lshl_add_u64 v[86:87], s[2:3], 0, v[30:31]
	v_mul_f32_e32 v61, 0x45800000, v53
	v_cndmask_b32_e32 v78, v53, v61, vcc
	v_mul_f32_e32 v53, 0x4b800000, v60
	v_cmp_gt_f32_e32 vcc, s0, v60
	v_pk_mul_f32 v[82:83], v[78:79], v[82:83] op_sel_hi:[0,1]
	v_pk_mul_f32 v[66:67], v[78:79], v[66:67] op_sel_hi:[0,1]
	v_cndmask_b32_e32 v53, v60, v53, vcc
	v_rsq_f32_e32 v53, v53
	v_pk_mul_f32 v[82:83], v[10:11], v[82:83]
	v_pk_mul_f32 v[66:67], v[12:13], v[66:67]
	v_cvt_pk_bf16_f32 v60, v82, v83
	v_cvt_pk_bf16_f32 v61, v66, v67
	s_waitcnt vmcnt(0)
	global_store_dwordx2 v[86:87], v[60:61], off
	v_mul_f32_e32 v60, 0x45800000, v53
	v_cndmask_b32_e32 v60, v53, v60, vcc
	v_pk_mul_f32 v[60:61], v[60:61], v[84:85] op_sel_hi:[0,1]
	v_pk_mul_f32 v[66:67], v[18:19], v[60:61]
	v_lshl_add_u64 v[60:61], s[2:3], 0, v[28:29]
	v_cvt_pk_bf16_f32 v53, v66, v67
	global_store_dword v[60:61], v53, off
	v_lshlrev_b64 v[60:61], 9, v[64:65]
	s_and_saveexec_b64 s[46:47], s[16:17]
	s_cbranch_execz .LBB0_1191
	v_readlane_b32 s0, v254, 25
	v_readlane_b32 s1, v254, 26
	s_load_dwordx2 s[0:1], s[0:1], 0x110
	v_lshlrev_b32_e32 v82, 2, v74
	v_mov_b32_e32 v83, v1
	s_waitcnt lgkmcnt(0)
	v_lshl_add_u64 v[84:85], s[0:1], 0, v[60:61]
	v_lshl_add_u64 v[82:83], v[84:85], 0, v[82:83]
	v_add_co_u32_e32 v82, vcc, 0x6000000, v82
	s_nop 1
	v_addc_co_u32_e32 v83, vcc, 0, v83, vcc
	global_store_dwordx2 v[82:83], v[66:67], off

.LBB0_1197:
	s_or_b64 exec, exec, s[16:17]
	v_and_b32_e32 v53, 63, v70
	v_lshrrev_b32_e32 v62, 6, v62
	v_cndmask_b32_e64 v53, v53, v62, s[12:13]
	v_lshlrev_b32_e32 v62, 16, v54
	v_and_b32_e32 v63, 0xffff0000, v54
	v_pk_mul_f32 v[64:65], v[62:63], v[62:63]
	v_lshlrev_b32_e32 v66, 16, v55
	v_and_b32_e32 v67, 0xffff0000, v55
	v_pk_mul_f32 v[54:55], v[66:67], v[66:67]
	v_add_f32_e32 v64, v64, v65
	v_add_f32_e32 v54, v54, v64
	v_add_f32_e32 v54, v55, v54
	s_nop 1
	v_add_f32_dpp v54, v54, v54 row_ror:8 row_mask:0xf bank_mask:0xf
	s_nop 1
	v_add_f32_dpp v54, v54, v54 row_ror:4 row_mask:0xf bank_mask:0xf
	s_nop 1
	v_add_f32_dpp v54, v54, v54 row_ror:2 row_mask:0xf bank_mask:0xf
	s_nop 1
	v_add_f32_dpp v54, v54, v54 row_ror:1 row_mask:0xf bank_mask:0xf
	s_mov_b32 s0, 0x800000
	v_lshl_or_b32 v53, v53, 4, v21
	v_lshlrev_b32_e32 v53, 3, v53
	s_mov_b64 s[46:47], s[28:29]
	s_waitcnt lgkmcnt(0)
	s_waitcnt lgkmcnt(0)
	s_waitcnt lgkmcnt(0)
	s_waitcnt lgkmcnt(0)
	v_fmamk_f32 v54, v54, 0x3c800000, v162
	v_cmp_gt_f32_e32 vcc, s0, v54
	v_mul_f32_e32 v55, 0x4b800000, v54
	s_nop 0
	v_cndmask_b32_e32 v54, v54, v55, vcc
	v_rsq_f32_e32 v54, v54
	s_nop 0
	v_mul_f32_e32 v55, 0x45800000, v54
	v_cndmask_b32_e32 v64, v54, v55, vcc
	v_pk_mul_f32 v[54:55], v[64:65], v[62:63] op_sel_hi:[0,1]
	v_pk_mul_f32 v[62:63], v[64:65], v[66:67] op_sel_hi:[0,1]
	v_pk_mul_f32 v[54:55], v[6:7], v[54:55]
	v_pk_mul_f32 v[62:63], v[8:9], v[62:63]
	s_and_saveexec_b64 s[16:17], s[14:15]
	s_cbranch_execz .LBB0_1199
	ds_read_b128 v[64:67], v53 offset:4112
	ds_read_b128 v[82:85], v53 offset:4096
	ds_bpermute_b32 v86, v77, v54
	ds_bpermute_b32 v87, v77, v55
	ds_bpermute_b32 v88, v77, v62
	ds_bpermute_b32 v89, v77, v63
	s_andn2_b64 s[46:47], s[28:29], exec
	s_waitcnt lgkmcnt(4)
	v_mov_b32_e32 v90, v83
	v_mov_b32_e32 v91, v85
	s_waitcnt lgkmcnt(2)
	v_pk_mul_f32 v[86:87], v[90:91], v[86:87]
	v_mov_b32_e32 v83, v84
	v_cndmask_b32_e64 v85, v87, -v87, s[10:11]
	v_cndmask_b32_e64 v84, v86, -v86, s[10:11]
	v_pk_fma_f32 v[54:55], v[54:55], v[82:83], v[84:85]
	v_mov_b32_e32 v82, v65
	v_mov_b32_e32 v83, v67
	s_waitcnt lgkmcnt(0)
	v_pk_mul_f32 v[82:83], v[82:83], v[88:89]
	v_mov_b32_e32 v65, v66
	v_cndmask_b32_e64 v67, v83, -v83, s[10:11]
	v_cndmask_b32_e64 v66, v82, -v82, s[10:11]
	v_pk_fma_f32 v[62:63], v[62:63], v[64:65], v[66:67]
.LBB0_1199:
	s_or_b64 exec, exec, s[16:17]
	v_cvt_pk_bf16_f32 v54, v54, v55
	v_cvt_pk_bf16_f32 v55, v62, v63
	global_store_dwordx2 v[16:17], v[54:55], off
	v_lshlrev_b32_e32 v16, 16, v14
	v_and_b32_e32 v17, 0xffff0000, v14
	v_pk_mul_f32 v[54:55], v[16:17], v[16:17]
	v_lshlrev_b32_e32 v62, 16, v15
	v_and_b32_e32 v63, 0xffff0000, v15
	v_pk_mul_f32 v[14:15], v[62:63], v[62:63]
	v_add_f32_e32 v54, v54, v55
	v_add_f32_e32 v14, v14, v54
	v_add_f32_e32 v14, v15, v14
	s_nop 1
	v_add_f32_dpp v14, v14, v14 row_ror:8 row_mask:0xf bank_mask:0xf
	s_nop 1
	v_add_f32_dpp v14, v14, v14 row_ror:4 row_mask:0xf bank_mask:0xf
	s_nop 1
	v_add_f32_dpp v14, v14, v14 row_ror:2 row_mask:0xf bank_mask:0xf
	s_nop 1
	v_add_f32_dpp v14, v14, v14 row_ror:1 row_mask:0xf bank_mask:0xf
	s_waitcnt lgkmcnt(0)
	s_waitcnt lgkmcnt(0)
	s_waitcnt lgkmcnt(0)
	s_waitcnt lgkmcnt(0)
	v_fmamk_f32 v14, v14, 0x3c800000, v162
	v_cmp_gt_f32_e32 vcc, s0, v14
	v_mul_f32_e32 v15, 0x4b800000, v14
	s_nop 0
	v_cndmask_b32_e32 v14, v14, v15, vcc
	v_rsq_f32_e32 v14, v14
	s_nop 0
	v_mul_f32_e32 v15, 0x45800000, v14
	v_cndmask_b32_e32 v54, v14, v15, vcc
	v_pk_mul_f32 v[14:15], v[54:55], v[16:17] op_sel_hi:[0,1]
	v_pk_mul_f32 v[16:17], v[54:55], v[62:63] op_sel_hi:[0,1]
	v_pk_mul_f32 v[14:15], v[2:3], v[14:15]
	v_pk_mul_f32 v[16:17], v[4:5], v[16:17]
	v_lshlrev_b32_e32 v54, 2, v72
	s_and_saveexec_b64 s[16:17], s[46:47]
	s_cbranch_execnz .LBB0_1204
	s_or_b64 exec, exec, s[16:17]
	s_and_saveexec_b64 s[16:17], s[14:15]
	s_cbranch_execnz .LBB0_1205

.LBB0_1208:
	v_and_b32_e32 v15, 0xffff0000, v43
	v_and_b32_e32 v14, s0, v42
	v_mov_b32_e32 v57, v15
	v_pk_mul_f32 v[14:15], v[14:15], v[14:15]
	v_and_b32_e32 v59, 0xffff0000, v42
	v_lshlrev_b32_e32 v58, 16, v42
	v_mul_f32_e32 v14, v59, v59
	v_lshlrev_b32_e32 v56, 16, v43
	v_pk_fma_f32 v[16:17], v[58:59], v[58:59], v[14:15] op_sel_hi:[1,1,0]
	v_lshlrev_b32_e32 v60, 16, v71
	v_and_b32_e32 v61, 0xffff0000, v71
	v_pk_fma_f32 v[16:17], v[56:57], v[56:57], v[16:17]
	v_pk_mul_f32 v[62:63], v[60:61], v[60:61]
	s_movk_i32 s0, 0x1fff
	v_mov_b32_e32 v14, v62
	v_pk_mov_b32 v[16:17], v[62:63], v[16:17] op_sel:[1,0]
	v_cmp_lt_i32_e64 s[16:17], s0, v50
	v_pk_add_f32 v[14:15], v[14:15], v[16:17]
	s_movk_i32 s0, 0x2000
	v_cmp_gt_i32_e64 s[14:15], s0, v50
	v_readlane_b32 s0, v254, 29
	v_readlane_b32 s1, v254, 30
	s_waitcnt lgkmcnt(0)
	s_nop 1
	v_add_f32_dpp v14, v14, v14 row_shr:1 row_mask:0xf bank_mask:0xf bound_ctrl:1
	v_add_f32_dpp v15, v15, v15 row_shr:1 row_mask:0xf bank_mask:0xf bound_ctrl:1
	s_nop 0
	v_add_f32_dpp v14, v14, v14 row_shr:2 row_mask:0xf bank_mask:0xf bound_ctrl:1
	v_add_f32_dpp v15, v15, v15 row_shr:2 row_mask:0xf bank_mask:0xf bound_ctrl:1
	s_nop 0
	v_add_f32_dpp v14, v14, v14 row_shr:4 row_mask:0xf bank_mask:0xf bound_ctrl:1
	v_add_f32_dpp v15, v15, v15 row_shr:4 row_mask:0xf bank_mask:0xf bound_ctrl:1
	s_nop 0
	v_add_f32_dpp v14, v14, v14 row_shr:8 row_mask:0xf bank_mask:0xf bound_ctrl:1
	v_add_f32_dpp v15, v15, v15 row_shr:8 row_mask:0xf bank_mask:0xf bound_ctrl:1
	s_nop 0
	v_add_f32_dpp v14, v14, v14 row_bcast:15 row_mask:0xa bank_mask:0xf
	v_add_f32_dpp v15, v15, v15 row_bcast:15 row_mask:0xa bank_mask:0xf
	s_nop 0
	v_add_f32_dpp v14, v14, v14 row_bcast:31 row_mask:0xc bank_mask:0xf
	v_add_f32_dpp v15, v15, v15 row_bcast:31 row_mask:0xc bank_mask:0xf
	s_nop 0
	v_readlane_b32 s98, v14, 63
	v_readlane_b32 s99, v15, 63
	s_nop 0
	v_mov_b32_e32 v14, s98
	v_mov_b32_e32 v15, s99
	s_mov_b32 s2, 0x800000
	v_mov_b32_e32 v53, v1
	s_waitcnt lgkmcnt(0)
	s_waitcnt lgkmcnt(0)
	v_mov_b32_e32 v16, v14
	v_mov_b32_e32 v17, v15
	v_ashrrev_i32_e32 v15, 7, v50
	v_and_b32_e32 v15, -2, v15
	v_cndmask_b32_e64 v15, 0, v15, s[14:15]
	v_add_u32_e32 v64, s0, v15
	s_waitcnt lgkmcnt(0)
	v_readlane_b32 s0, v254, 33
	v_ashrrev_i32_e32 v65, 31, v64
	v_readlane_b32 s1, v254, 34
	v_cndmask_b32_e64 v14, v213, v214, s[14:15]
	s_waitcnt lgkmcnt(0)
	v_mov_b32_e32 v62, v16
	v_mov_b32_e32 v63, v17
	v_lshlrev_b64 v[16:17], 8, v[64:65]
	v_mov_b64_e32 v[64:65], s[0:1]
	s_brev_b32 s0, 60
	s_mov_b32 s1, 0x3b800000
	s_waitcnt lgkmcnt(0)
	v_and_b32_e32 v14, v14, v50
	v_mov_b32_e32 v15, v1
	v_pk_fma_f32 v[62:63], v[62:63], s[0:1], v[162:163] op_sel_hi:[1,1,0]
	v_lshl_add_u64 v[16:17], v[16:17], 0, v[14:15]
	v_mul_f32_e32 v15, 0x4b800000, v63
	v_cmp_gt_f32_e32 vcc, s2, v63
	s_movk_i32 s0, 0x300
	v_mad_i64_i32 v[64:65], s[0:1], v50, s0, v[64:65]
	v_cndmask_b32_e32 v15, v63, v15, vcc
	v_rsq_f32_e32 v15, v15
	v_lshl_add_u64 v[66:67], v[64:65], 0, v[0:1]
	v_lshl_add_u64 v[52:53], v[64:65], 0, v[52:53]
	v_mul_f32_e32 v0, 0x45800000, v15
	v_cndmask_b32_e32 v0, v15, v0, vcc
	v_pk_mul_f32 v[58:59], v[0:1], v[58:59] op_sel_hi:[0,1]
	v_pk_mul_f32 v[56:57], v[0:1], v[56:57] op_sel_hi:[0,1]
	v_mul_f32_e32 v0, 0x4b800000, v62
	v_cmp_gt_f32_e32 vcc, s2, v62
	v_pk_mul_f32 v[58:59], v[10:11], v[58:59]
	v_pk_mul_f32 v[56:57], v[12:13], v[56:57]
	v_cndmask_b32_e32 v0, v62, v0, vcc
	v_rsq_f32_e32 v0, v0
	v_cvt_pk_bf16_f32 v58, v58, v59
	v_cvt_pk_bf16_f32 v59, v56, v57
	global_store_dwordx2 v[66:67], v[58:59], off
	v_mul_f32_e32 v15, 0x45800000, v0
	v_cndmask_b32_e32 v0, v0, v15, vcc
	v_pk_mul_f32 v[56:57], v[0:1], v[60:61] op_sel_hi:[0,1]
	v_pk_mul_f32 v[56:57], v[18:19], v[56:57]
	s_nop 0
	v_cvt_pk_bf16_f32 v0, v56, v57
	global_store_dword v[52:53], v0, off offset:512
	v_lshlrev_b64 v[52:53], 9, v[16:17]
	s_and_saveexec_b64 s[46:47], s[14:15]
	s_cbranch_execz .LBB0_1210
	v_readlane_b32 s0, v254, 25
	v_readlane_b32 s1, v254, 26
	s_load_dwordx2 s[0:1], s[0:1], 0x110
	v_lshlrev_b32_e32 v0, 2, v74
	s_waitcnt lgkmcnt(0)
	v_lshl_add_u64 v[58:59], s[0:1], 0, v[52:53]
	v_lshl_add_u64 v[58:59], v[58:59], 0, v[0:1]
	v_add_co_u32_e32 v58, vcc, 0x6000000, v58
	s_nop 1
	v_addc_co_u32_e32 v59, vcc, 0, v59, vcc
	global_store_dwordx2 v[58:59], v[56:57], off

.LBB0_1216:
	s_or_b64 exec, exec, s[46:47]
	v_and_b32_e32 v0, 63, v50
	v_lshrrev_b32_e32 v14, 6, v14
	v_cndmask_b32_e64 v0, v0, v14, s[12:13]
	v_lshlrev_b32_e32 v14, 16, v46
	v_and_b32_e32 v15, 0xffff0000, v46
	v_pk_mul_f32 v[16:17], v[14:15], v[14:15]
	v_lshlrev_b32_e32 v56, 16, v47
	v_and_b32_e32 v57, 0xffff0000, v47
	v_lshl_or_b32 v55, v0, 4, v21
	v_pk_mul_f32 v[58:59], v[56:57], v[56:57]
	v_add_f32_e32 v0, v16, v17
	v_add_f32_e32 v0, v58, v0
	v_add_f32_e32 v0, v59, v0
	s_nop 1
	v_add_f32_dpp v0, v0, v0 row_ror:8 row_mask:0xf bank_mask:0xf
	s_nop 1
	v_add_f32_dpp v0, v0, v0 row_ror:4 row_mask:0xf bank_mask:0xf
	s_nop 1
	v_add_f32_dpp v0, v0, v0 row_ror:2 row_mask:0xf bank_mask:0xf
	s_nop 1
	v_add_f32_dpp v0, v0, v0 row_ror:1 row_mask:0xf bank_mask:0xf
	s_mov_b32 s0, 0x800000
	s_mov_b64 s[48:49], s[28:29]
	s_waitcnt lgkmcnt(0)
	s_waitcnt lgkmcnt(0)
	s_waitcnt lgkmcnt(0)
	s_waitcnt lgkmcnt(0)
	v_fmamk_f32 v0, v0, 0x3c800000, v162
	v_cmp_gt_f32_e32 vcc, s0, v0
	v_mul_f32_e32 v16, 0x4b800000, v0
	s_nop 0
	v_cndmask_b32_e32 v0, v0, v16, vcc
	v_rsq_f32_e32 v0, v0
	s_nop 0
	v_mul_f32_e32 v16, 0x45800000, v0
	v_cndmask_b32_e32 v0, v0, v16, vcc
	v_pk_mul_f32 v[14:15], v[0:1], v[14:15] op_sel_hi:[0,1]
	v_pk_mul_f32 v[16:17], v[0:1], v[56:57] op_sel_hi:[0,1]
	v_pk_mul_f32 v[14:15], v[6:7], v[14:15]
	v_pk_mul_f32 v[16:17], v[8:9], v[16:17]
	v_lshlrev_b32_e32 v0, 3, v55
	s_and_saveexec_b64 s[46:47], s[16:17]
	s_cbranch_execz .LBB0_1218
	ds_read_b128 v[56:59], v0 offset:4112
	ds_read_b128 v[60:63], v0 offset:4096
	ds_bpermute_b32 v64, v77, v14
	ds_bpermute_b32 v65, v77, v15
	ds_bpermute_b32 v66, v77, v16
	ds_bpermute_b32 v67, v77, v17
	s_andn2_b64 s[48:49], s[28:29], exec
	s_waitcnt lgkmcnt(4)
	v_mov_b32_e32 v82, v61
	v_mov_b32_e32 v83, v63
	s_waitcnt lgkmcnt(2)
	v_pk_mul_f32 v[64:65], v[82:83], v[64:65]
	v_mov_b32_e32 v61, v62
	v_cndmask_b32_e64 v63, v65, -v65, s[10:11]
	v_cndmask_b32_e64 v62, v64, -v64, s[10:11]
	v_pk_fma_f32 v[14:15], v[14:15], v[60:61], v[62:63]
	v_mov_b32_e32 v60, v57
	v_mov_b32_e32 v61, v59
	s_waitcnt lgkmcnt(0)
	v_pk_mul_f32 v[60:61], v[60:61], v[66:67]
	v_mov_b32_e32 v57, v58
	v_cndmask_b32_e64 v59, v61, -v61, s[10:11]
	v_cndmask_b32_e64 v58, v60, -v60, s[10:11]
	v_pk_fma_f32 v[16:17], v[16:17], v[56:57], v[58:59]
.LBB0_1218:
	s_or_b64 exec, exec, s[46:47]
	v_lshlrev_b64 v[50:51], 10, v[50:51]
	v_lshl_add_u64 v[50:51], v[24:25], 0, v[50:51]
	v_cvt_pk_bf16_f32 v14, v14, v15
	v_cvt_pk_bf16_f32 v15, v16, v17
	global_store_dwordx2 v[50:51], v[14:15], off
	v_lshlrev_b32_e32 v14, 16, v44
	v_and_b32_e32 v15, 0xffff0000, v44
	v_pk_mul_f32 v[16:17], v[14:15], v[14:15]
	v_lshlrev_b32_e32 v56, 16, v45
	v_and_b32_e32 v57, 0xffff0000, v45
	v_pk_mul_f32 v[58:59], v[56:57], v[56:57]
	v_add_f32_e32 v16, v16, v17
	v_add_f32_e32 v16, v58, v16
	v_add_f32_e32 v16, v59, v16
	s_nop 1
	v_add_f32_dpp v16, v16, v16 row_ror:8 row_mask:0xf bank_mask:0xf
	s_nop 1
	v_add_f32_dpp v16, v16, v16 row_ror:4 row_mask:0xf bank_mask:0xf
	s_nop 1
	v_add_f32_dpp v16, v16, v16 row_ror:2 row_mask:0xf bank_mask:0xf
	s_nop 1
	v_add_f32_dpp v16, v16, v16 row_ror:1 row_mask:0xf bank_mask:0xf
	s_waitcnt lgkmcnt(0)
	s_waitcnt lgkmcnt(0)
	s_waitcnt lgkmcnt(0)
	s_waitcnt lgkmcnt(0)
	v_fmamk_f32 v16, v16, 0x3c800000, v162
	v_cmp_gt_f32_e32 vcc, s0, v16
	v_mul_f32_e32 v17, 0x4b800000, v16
	s_nop 0
	v_cndmask_b32_e32 v16, v16, v17, vcc
	v_rsq_f32_e32 v16, v16
	s_nop 0
	v_mul_f32_e32 v17, 0x45800000, v16
	v_cndmask_b32_e32 v16, v16, v17, vcc
	v_pk_mul_f32 v[14:15], v[16:17], v[14:15] op_sel_hi:[0,1]
	v_pk_mul_f32 v[16:17], v[16:17], v[56:57] op_sel_hi:[0,1]
	v_pk_mul_f32 v[14:15], v[2:3], v[14:15]
	v_pk_mul_f32 v[16:17], v[4:5], v[16:17]
	s_and_saveexec_b64 s[46:47], s[48:49]
	s_cbranch_execnz .LBB0_1222
	s_or_b64 exec, exec, s[46:47]
	s_and_saveexec_b64 s[46:47], s[16:17]
	s_cbranch_execnz .LBB0_1223
